# x12: group A body with pure-MFMA QK phase then softmax-finish VALU, PV interleaved with max/exp; group B as v13; canonical max removed; aligned loop bodies
# speedup vs baseline: 1.0041x; 1.0041x over previous
; #define SBAR() __builtin_amdgcn_sched_barrier(0)
; #define SLOAD(i, j) do { const long kr_ = KROW(j); sr_[i].vs0 = ld8(Vp + (kr_ + sr) * ldv + sc); sr_[i].ks0 = ld8(Kp + (kr_ + sr) * ldk + sc); \
;     if (DQK == 96) sr_[i].ks1 = ld8(Kp + (kr_ + sr2) * ldk + sc2); } while (0)
; __device__ __forceinline__ void finishSM(f32x16& p0, f32x16& p1, float alpha, float& l_reg, bf16x8& pa0, bf16x8& pa1, bf16x8& pa2, bf16x8& pa3) {
; #pragma unroll
;   for (int r = 0; r < 16; ++r) p1[r] = __builtin_amdgcn_exp2f(p1[r]);
;   float ps = 0;
; #pragma unroll
;   for (int r = 0; r < 16; ++r) ps += p0[r];
; #pragma unroll
;   for (int r = 0; r < 16; ++r) ps += p1[r];
;   { auto rr = __builtin_amdgcn_permlane32_swap(__float_as_uint(ps), __float_as_uint(ps), false, false);
;     ps = __uint_as_float(rr[0]) + __uint_as_float(rr[1]); }
;   l_reg = l_reg * alpha + ps;
;     ...
;   PK4(p0, 0, pa0); PK4(p0, 8, pa1); PK4(p1, 0, pa2); PK4(p1, 8, pa3);
;     ...
; }
; template <int DQK> __device__ __forceinline__ void qkt(f32x16& p0, f32x16& p1, const char* Ks, const bf16x8* qr, int r32, int hi) {
;   p0 = f32x16{}; p1 = f32x16{};
; #pragma unroll
;   for (int d0 = 0; d0 < DQK / 16; ++d0) { int cb = (d0 * 16 + hi * 8) * 2;
;     bf16x8 b0 = *reinterpret_cast<const bf16x8*>(Ks + KSWZ(r32, cb));
;     bf16x8 b1 = *reinterpret_cast<const bf16x8*>(Ks + KSWZ(32 + r32, cb));
;     p0 = __builtin_amdgcn_mfma_f32_32x32x16_bf16(b0, qr[d0], p0, 0, 0, 0);
;     p1 = __builtin_amdgcn_mfma_f32_32x32x16_bf16(b1, qr[d0], p1, 0, 0, 0); }
; }
; template <int DQK, int MODE, int ldq, int ldk, int ldv> ...
;     ...
;   for (int j = 1; j + 1 < NT; j += 2) {
;     SBAR(); qkt<DQK>(pB0, pB1, K_lds + SHM_K, qr, r32, hi);
;     finishSM(pA0, pA1, alA, l_reg, pa0, pa1, pa2, pa3); SBAR();
;     SLOAD(SO, j + 2); SBAR();
.LBB0_300:
	s_add_i32 s25, s11, -3
	s_cmp_lg_u32 s32, 0
	s_cbranch_scc1 .Lmy_h1B
	ds_read_b128 v[32:35], v148 offset:49152
	ds_read_b128 v[36:39], v148 offset:57344
	ds_read_b128 v[164:167], v152 offset:49152
	ds_read_b128 v[168:171], v152 offset:57344
	s_waitcnt lgkmcnt(3)
	v_mfma_f32_32x32x16_bf16 v[48:63], v[32:35], v[84:87], 0
	s_waitcnt lgkmcnt(2)
	v_mfma_f32_32x32x16_bf16 v[32:47], v[36:39], v[84:87], 0
	s_waitcnt lgkmcnt(1)
	v_mfma_f32_32x32x16_bf16 v[48:63], v[164:167], v[80:83], v[48:63]
	s_waitcnt lgkmcnt(0)
	v_mfma_f32_32x32x16_bf16 v[32:47], v[168:171], v[80:83], v[32:47]
	ds_read_b128 v[164:167], v151 offset:49152
	ds_read_b128 v[168:171], v151 offset:57344
	s_waitcnt lgkmcnt(1)
	v_mfma_f32_32x32x16_bf16 v[48:63], v[164:167], v[76:79], v[48:63]
	s_waitcnt lgkmcnt(0)
	v_mfma_f32_32x32x16_bf16 v[32:47], v[168:171], v[76:79], v[32:47]
	ds_read_b128 v[164:167], v149 offset:49152
	ds_read_b128 v[168:171], v149 offset:57344
	s_waitcnt lgkmcnt(1)
	v_mfma_f32_32x32x16_bf16 v[48:63], v[164:167], v[72:75], v[48:63]
	s_waitcnt lgkmcnt(0)
	v_mfma_f32_32x32x16_bf16 v[32:47], v[168:171], v[72:75], v[32:47]
	ds_read_b128 v[164:167], v150 offset:49152
	ds_read_b128 v[168:171], v150 offset:57344
	s_waitcnt lgkmcnt(1)
	v_mfma_f32_32x32x16_bf16 v[48:63], v[164:167], v[68:71], v[48:63]
	s_waitcnt lgkmcnt(0)
	v_mfma_f32_32x32x16_bf16 v[32:47], v[168:171], v[68:71], v[32:47]
	ds_read_b128 v[164:167], v153 offset:49152
	ds_read_b128 v[168:171], v153 offset:57344
	s_waitcnt vmcnt(0)
	ds_write_b128 v146, v[88:91] offset:32768
	ds_write_b128 v147, v[96:99] offset:32768
	ds_write_b128 v145, v[92:95] offset:16384
	s_waitcnt lgkmcnt(4)
	v_mfma_f32_32x32x16_bf16 v[48:63], v[164:167], v[64:67], v[48:63]
	s_waitcnt lgkmcnt(3)
	v_mfma_f32_32x32x16_bf16 v[32:47], v[168:171], v[64:67], v[32:47]
	ds_read_b64_tr_b16 v[192:193], v144 offset:0
	ds_read_b64_tr_b16 v[194:195], v144 offset:0x800
	ds_read_b64_tr_b16 v[196:197], v144 offset:0x1000
	ds_read_b64_tr_b16 v[198:199], v144 offset:0x1800
	ds_read_b64_tr_b16 v[200:201], v144 offset:0x2000
	ds_read_b64_tr_b16 v[202:203], v144 offset:0x2800
	ds_read_b64_tr_b16 v[210:211], v144 offset:0x3000
	ds_read_b64_tr_b16 v[212:213], v144 offset:0x3800
	v_exp_f32_e32 v117, v114
	v_exp_f32_e32 v157, v115
	v_exp_f32_e32 v108, v108
	v_exp_f32_e32 v109, v109
	v_exp_f32_e32 v104, v104
	v_exp_f32_e32 v105, v105
	v_exp_f32_e32 v102, v102
	v_exp_f32_e32 v103, v103
	v_exp_f32_e32 v110, v110
	v_exp_f32_e32 v111, v111
	v_exp_f32_e32 v106, v106
	v_exp_f32_e32 v107, v107
	v_exp_f32_e32 v100, v100
	v_exp_f32_e32 v101, v101
	v_exp_f32_e32 v164, v112
	v_add_f32_e32 v112, 0, v126
	v_add_f32_e32 v112, v160, v112
	v_add_f32_e32 v112, v127, v112
	v_add_f32_e32 v112, v161, v112
	v_add_f32_e32 v112, v158, v112
	v_add_f32_e32 v112, v162, v112
	v_add_f32_e32 v112, v159, v112
	v_add_f32_e32 v112, v163, v112
	v_add_f32_e32 v112, v118, v112
	v_add_f32_e32 v112, v121, v112
	v_add_f32_e32 v112, v119, v112
	v_add_f32_e32 v112, v122, v112
	v_add_f32_e32 v112, v120, v112
	v_add_f32_e32 v112, v123, v112
	v_add_f32_e32 v112, v124, v112
	v_exp_f32_e32 v165, v113
	v_add_f32_e32 v112, v125, v112
	v_add_f32_e32 v112, v117, v112
	v_add_f32_e32 v112, v157, v112
	v_add_f32_e32 v112, v164, v112
	v_add_f32_e32 v112, v165, v112
	v_add_f32_e32 v112, v108, v112
	v_add_f32_e32 v112, v109, v112
	v_add_f32_e32 v112, v104, v112
	v_add_f32_e32 v112, v105, v112
	v_add_f32_e32 v112, v102, v112
	v_add_f32_e32 v112, v103, v112
	v_add_f32_e32 v112, v110, v112
	v_add_f32_e32 v112, v111, v112
	v_add_f32_e32 v112, v106, v112
	v_add_f32_e32 v112, v107, v112
	v_add_f32_e32 v112, v100, v112
	v_add_f32_e32 v155, v101, v112
	v_mov_b32_e32 v156, v155
	v_cvt_pk_bf16_f32 v214, v126, v160
	v_cvt_pk_bf16_f32 v215, v127, v161
	v_cvt_pk_bf16_f32 v216, v158, v162
	s_nop 1
	v_permlane32_swap_b32_e32 v155, v156
	v_cvt_pk_bf16_f32 v217, v159, v163
	v_permlane32_swap_b32_e32 v214, v216
	v_cvt_pk_bf16_f32 v218, v118, v121
	v_cvt_pk_bf16_f32 v219, v119, v122
	v_cvt_pk_bf16_f32 v220, v120, v123
	v_cvt_pk_bf16_f32 v221, v124, v125
	v_cvt_pk_bf16_f32 v222, v117, v157
	v_cvt_pk_bf16_f32 v223, v164, v165
	v_cvt_pk_bf16_f32 v224, v108, v109
	v_cvt_pk_bf16_f32 v225, v104, v105
	v_cvt_pk_bf16_f32 v226, v102, v103
	v_cvt_pk_bf16_f32 v227, v110, v111
	v_cvt_pk_bf16_f32 v228, v106, v107
	v_cvt_pk_bf16_f32 v229, v100, v101
	v_permlane32_swap_b32_e32 v215, v217
	v_permlane32_swap_b32_e32 v218, v220
	v_permlane32_swap_b32_e32 v219, v221
	v_permlane32_swap_b32_e32 v222, v224
	v_permlane32_swap_b32_e32 v223, v225
	v_permlane32_swap_b32_e32 v226, v228
	v_permlane32_swap_b32_e32 v227, v229
	s_cmpk_lt_u32 s25, 0x7e
	s_cselect_b32 s0, 0, 0xffffff80
	s_cselect_b32 s1, s10, s24
	s_add_i32 s0, s0, s11
	s_lshl_b32 s0, s0, 6
	s_add_i32 s0, s0, s1
	s_sub_i32 s0, s0, 64
	s_ashr_i32 s1, s0, 31
	s_cmpk_lt_u32 s25, 0x7f
	s_cselect_b32 s98, 0, 0xffffff80
	s_cselect_b32 s99, s10, s24
	s_add_i32 s98, s98, s11
	s_lshl_b32 s98, s98, 6
	s_add_i32 s98, s98, s99
	s_addk_i32 s98, 0xff80
	s_ashr_i32 s99, s98, 31
	v_lshl_add_u64 v[100:101], s[0:1], 0, v[130:131]
	v_lshl_add_u64 v[104:105], s[98:99], 0, v[130:131]
	v_lshlrev_b64 v[104:105], 9, v[104:105]
	v_lshl_add_u64 v[104:105], v[134:135], 0, v[104:105]
	v_mad_u64_u32 v[102:103], s[12:13], v100, s70, v[136:137]
	v_or_b32_e32 v106, s0, v132
	v_mad_i32_i24 v103, v101, s70, v103
	v_mad_i64_i32 v[106:107], s[0:1], v106, s70, v[138:139]
	global_load_dwordx4 v[184:187], v[102:103], off
	s_nop 0
	global_load_dwordx4 v[188:191], v[104:105], off
	s_nop 0
	global_load_dwordx4 v[230:233], v[106:107], off offset:128
	s_waitcnt lgkmcnt(0)
; #define SBAR() __builtin_amdgcn_sched_barrier(0)
; template <int DQK> __device__ __forceinline__ void partialSM(f32x16& p0, f32x16& p1, float& m_reg, float& mn, float& alpha) {
;   constexpr float SCALE = (DQK == 96) ? 0.10206207261596577f : 0.125f;
;   constexpr float C = SCALE * 1.4426950408889634f;
;   float pmax = p0[0];
; #pragma unroll
;   for (int r = 1; r < 16; ++r) pmax = fmaxf(pmax, p0[r]);
; #pragma unroll
;   for (int r = 0; r < 16; ++r) pmax = fmaxf(pmax, p1[r]);
;   { auto rr = __builtin_amdgcn_permlane32_swap(__float_as_uint(pmax), __float_as_uint(pmax), false, false);
;     pmax = fmaxf(__uint_as_float(rr[0]), __uint_as_float(rr[1])); }
;   if (__builtin_expect(__all(pmax - m_reg <= THR / SCALE), 1)) { mn = m_reg; alpha = 1.f; }
;   else { mn = fmaxf(m_reg, pmax); alpha = __builtin_amdgcn_exp2f((m_reg - mn) * C); m_reg = mn; }
;   float mnC = -mn * C;
; #pragma unroll
;   for (int r = 0; r < 16; ++r) p0[r] = fmaf(p0[r], C, mnC);
; #pragma unroll
;   for (int r = 0; r < 16; ++r) p1[r] = fmaf(p1[r], C, mnC);
; #pragma unroll
;   for (int r = 0; r < 16; ++r) p0[r] = __builtin_amdgcn_exp2f(p0[r]);
; }
; template <int D0> __device__ __forceinline__ void pv_one(f32x16& od, int vb, bf16x8 pa0, bf16x8 pa1, bf16x8 pa2, bf16x8 pa3) {
;   const s16x4 l0 = tr_read<v_rd_off(D0, 0, 0)>(vb), h0 = tr_read<v_rd_off(D0, 0, 1)>(vb), l1 = tr_read<v_rd_off(D0, 1, 0)>(vb), h1 = tr_read<v_rd_off(D0, 1, 1)>(vb);
;   const s16x4 l2 = tr_read<v_rd_off(D0, 2, 0)>(vb), h2 = tr_read<v_rd_off(D0, 2, 1)>(vb), l3 = tr_read<v_rd_off(D0, 3, 0)>(vb), h3 = tr_read<v_rd_off(D0, 3, 1)>(vb);
;   asm volatile("s_waitcnt lgkmcnt(0)" ::: "memory"); SBAR();
;   od = __builtin_amdgcn_mfma_f32_32x32x16_bf16(pa0, PKLH(l0, h0), od, 0, 0, 0);
;   od = __builtin_amdgcn_mfma_f32_32x32x16_bf16(pa1, PKLH(l1, h1), od, 0, 0, 0);
;   od = __builtin_amdgcn_mfma_f32_32x32x16_bf16(pa2, PKLH(l2, h2), od, 0, 0, 0);
;   od = __builtin_amdgcn_mfma_f32_32x32x16_bf16(pa3, PKLH(l3, h3), od, 0, 0, 0);
; }
; __device__ __forceinline__ void pv_d0(f32x16* o, int vb, bf16x8 pa0, bf16x8 pa1, bf16x8 pa2, bf16x8 pa3) {
;   pv_one<0>(o[0], vb, pa0, pa1, pa2, pa3); pv_one<1>(o[1], vb, pa0, pa1, pa2, pa3);
; }
	s_nop 0
	v_mfma_f32_32x32x16_bf16 v[0:15], v[214:217], v[192:195], v[0:15]
	ds_read_b64_tr_b16 v[192:193], v144 offset:0x200
	ds_read_b64_tr_b16 v[194:195], v144 offset:0xa00
	v_max_f32_e32 v112, v48, v49
	v_max3_f32 v112, v112, v50, v51
	v_max3_f32 v112, v112, v52, v53
	v_max3_f32 v112, v112, v54, v55
	v_max3_f32 v112, v112, v56, v57
	v_max3_f32 v112, v112, v58, v59
	v_max3_f32 v112, v112, v60, v61
	v_max3_f32 v112, v112, v62, v63
	v_mfma_f32_32x32x16_bf16 v[0:15], v[218:221], v[196:199], v[0:15]
	ds_read_b64_tr_b16 v[196:197], v144 offset:0x1200
	ds_read_b64_tr_b16 v[198:199], v144 offset:0x1a00
	v_max3_f32 v112, v112, v32, v33
	v_max3_f32 v112, v112, v34, v35
	v_max3_f32 v112, v112, v36, v37
	v_max3_f32 v112, v112, v38, v39
	v_max3_f32 v112, v112, v40, v41
	v_max3_f32 v112, v112, v42, v43
	v_max3_f32 v112, v112, v44, v45
	v_max3_f32 v112, v112, v46, v47
	v_mfma_f32_32x32x16_bf16 v[0:15], v[222:225], v[200:203], v[0:15]
	ds_read_b64_tr_b16 v[200:201], v144 offset:0x2200
	ds_read_b64_tr_b16 v[202:203], v144 offset:0x2a00
	v_mov_b32_e32 v113, v112
	s_nop 1
	v_permlane32_swap_b32_e32 v112, v113
	v_max_f32_e32 v112, v112, v113
	v_sub_f32_e32 v113, v112, v116
	v_cmp_ge_f32_e32 vcc, s80, v113
	v_max_f32_e32 v112, v116, v112
	v_sub_f32_e32 v113, v116, v112
	v_mfma_f32_32x32x16_bf16 v[0:15], v[226:229], v[210:213], v[0:15]
	ds_read_b64_tr_b16 v[210:211], v144 offset:0x3200
	ds_read_b64_tr_b16 v[212:213], v144 offset:0x3a00
	v_mul_f32_e32 v113, 0x3e16c740, v113
	v_exp_f32_e32 v113, v113
	s_cmp_eq_u64 vcc, exec
	s_cselect_b64 s[0:1], -1, 0
	v_cndmask_b32_e64 v157, v113, 1.0, s[0:1]
	v_cmp_gt_f32_e32 vcc, 1.0, v157
	s_waitcnt lgkmcnt(0)
	v_mfma_f32_32x32x16_bf16 v[16:31], v[214:217], v[192:195], v[16:31]
	v_cndmask_b32_e64 v158, v112, v116, s[0:1]
	v_mul_f32_e32 v159, 0xbe16c740, v158
	v_fmamk_f32 v48, v48, 0x3e16c740, v159
	v_fmamk_f32 v49, v49, 0x3e16c740, v159
	v_fmamk_f32 v50, v50, 0x3e16c740, v159
	v_fmamk_f32 v51, v51, 0x3e16c740, v159
	v_fmamk_f32 v52, v52, 0x3e16c740, v159
	v_fmamk_f32 v53, v53, 0x3e16c740, v159
	v_fmamk_f32 v54, v54, 0x3e16c740, v159
	v_fmamk_f32 v55, v55, 0x3e16c740, v159
	v_fmamk_f32 v56, v56, 0x3e16c740, v159
	v_fmamk_f32 v57, v57, 0x3e16c740, v159
	v_fmamk_f32 v58, v58, 0x3e16c740, v159
	v_mfma_f32_32x32x16_bf16 v[16:31], v[218:221], v[196:199], v[16:31]
	v_fmamk_f32 v59, v59, 0x3e16c740, v159
	v_fmamk_f32 v60, v60, 0x3e16c740, v159
	v_fmamk_f32 v61, v61, 0x3e16c740, v159
	v_fmamk_f32 v62, v62, 0x3e16c740, v159
	v_fmamk_f32 v63, v63, 0x3e16c740, v159
	v_exp_f32_e32 v112, v48
	v_exp_f32_e32 v127, v49
	v_exp_f32_e32 v113, v50
	v_exp_f32_e32 v126, v51
	v_exp_f32_e32 v114, v52
	v_exp_f32_e32 v125, v53
	v_exp_f32_e32 v115, v54
	v_exp_f32_e32 v124, v55
	v_mfma_f32_32x32x16_bf16 v[16:31], v[222:225], v[200:203], v[16:31]
	v_exp_f32_e32 v116, v56
	v_exp_f32_e32 v123, v57
	v_exp_f32_e32 v117, v58
	v_exp_f32_e32 v122, v59
	v_exp_f32_e32 v118, v60
	v_exp_f32_e32 v121, v61
	v_exp_f32_e32 v119, v62
	v_exp_f32_e32 v120, v63
	v_fmamk_f32 v164, v42, 0x3e16c740, v159
	v_fmamk_f32 v165, v43, 0x3e16c740, v159
	v_fmamk_f32 v167, v32, 0x3e16c740, v159
	v_fmamk_f32 v168, v33, 0x3e16c740, v159
	v_fmamk_f32 v169, v34, 0x3e16c740, v159
	v_mfma_f32_32x32x16_bf16 v[16:31], v[226:229], v[210:213], v[16:31]
	v_fmamk_f32 v170, v35, 0x3e16c740, v159
	v_fmamk_f32 v171, v36, 0x3e16c740, v159
	v_fmamk_f32 v172, v37, 0x3e16c740, v159
	v_fmamk_f32 v160, v38, 0x3e16c740, v159
	v_fmamk_f32 v161, v39, 0x3e16c740, v159
	v_fmamk_f32 v162, v40, 0x3e16c740, v159
	v_fmamk_f32 v163, v41, 0x3e16c740, v159
	v_fmamk_f32 v166, v44, 0x3e16c740, v159
	v_fmamk_f32 v173, v45, 0x3e16c740, v159
	v_fmamk_f32 v174, v46, 0x3e16c740, v159
	v_fmac_f32_e32 v159, 0x3e16c740, v47
	s_cbranch_vccz .LBB0_304
	s_and_saveexec_b64 s[12:13], s[4:5]
	ds_write_b32 v141, v157 offset:128
	s_or_b64 exec, exec, s[12:13]
	s_waitcnt lgkmcnt(0)
	ds_read_b128 v[192:195], v129 offset:224
	ds_read_b128 v[196:199], v129 offset:192
	ds_read_b128 v[200:203], v129 offset:160
	ds_read_b128 v[210:213], v129 offset:128
	s_waitcnt lgkmcnt(3)
	v_pk_mul_f32 v[14:15], v[14:15], v[194:195]
	s_waitcnt lgkmcnt(2)
	v_pk_mul_f32 v[10:11], v[10:11], v[198:199]
	s_waitcnt lgkmcnt(1)
	v_pk_mul_f32 v[6:7], v[6:7], v[202:203]
	s_waitcnt lgkmcnt(0)
	v_pk_mul_f32 v[2:3], v[2:3], v[212:213]
	v_pk_mul_f32 v[12:13], v[12:13], v[192:193]
	v_pk_mul_f32 v[8:9], v[8:9], v[196:197]
	v_pk_mul_f32 v[4:5], v[4:5], v[200:201]
	v_pk_mul_f32 v[0:1], v[0:1], v[210:211]
	v_pk_mul_f32 v[30:31], v[30:31], v[194:195]
	v_pk_mul_f32 v[26:27], v[26:27], v[198:199]
	v_pk_mul_f32 v[22:23], v[22:23], v[202:203]
	v_pk_mul_f32 v[18:19], v[18:19], v[212:213]
	v_pk_mul_f32 v[28:29], v[28:29], v[192:193]
	v_pk_mul_f32 v[24:25], v[24:25], v[196:197]
	v_pk_mul_f32 v[20:21], v[20:21], v[200:201]
	v_pk_mul_f32 v[16:17], v[16:17], v[210:211]
; #define SBAR() __builtin_amdgcn_sched_barrier(0)
; #define SLOAD(i, j) do { const long kr_ = KROW(j); sr_[i].vs0 = ld8(Vp + (kr_ + sr) * ldv + sc); sr_[i].ks0 = ld8(Kp + (kr_ + sr) * ldk + sc); \
;     if (DQK == 96) sr_[i].ks1 = ld8(Kp + (kr_ + sr2) * ldk + sc2); } while (0)
; #define SWRITE(b, i) do { *(bf16x8*)(V_lds + (b) * SHM_V + vst0) = sr_[i].vs0; *(bf16x8*)(K_lds + (b) * SHM_K + kst0) = sr_[i].ks0; \
;     if (DQK == 96) *(bf16x8*)(K_lds + (b) * SHM_K + kst1) = sr_[i].ks1; } while (0)
; #define RESC(a) do { if (__any((a) < 1.f)) { if (hi == 0) al_l[r32] = (a); asm volatile("s_waitcnt lgkmcnt(0)" ::: "memory"); \
;     _Pragma("unroll") for (int d = 0; d < 2; ++d) _Pragma("unroll") for (int r = 0; r < 16; ++r) o[d][r] *= al_l[crow(r, hi)]; } } while (0)
; __device__ __forceinline__ void finishSM(f32x16& p0, f32x16& p1, float alpha, float& l_reg, bf16x8& pa0, bf16x8& pa1, bf16x8& pa2, bf16x8& pa3) {
; #pragma unroll
;   for (int r = 0; r < 16; ++r) p1[r] = __builtin_amdgcn_exp2f(p1[r]);
;   float ps = 0;
; #pragma unroll
;   for (int r = 0; r < 16; ++r) ps += p0[r];
; #pragma unroll
;   for (int r = 0; r < 16; ++r) ps += p1[r];
;   { auto rr = __builtin_amdgcn_permlane32_swap(__float_as_uint(ps), __float_as_uint(ps), false, false);
;     ps = __uint_as_float(rr[0]) + __uint_as_float(rr[1]); }
;   l_reg = l_reg * alpha + ps;
;     ...
;   PK4(p0, 0, pa0); PK4(p0, 8, pa1); PK4(p1, 0, pa2); PK4(p1, 8, pa3);
;     ...
; }
; template <int DQK> __device__ __forceinline__ void qkt(f32x16& p0, f32x16& p1, const char* Ks, const bf16x8* qr, int r32, int hi) {
;   p0 = f32x16{}; p1 = f32x16{};
; #pragma unroll
;   for (int d0 = 0; d0 < DQK / 16; ++d0) { int cb = (d0 * 16 + hi * 8) * 2;
;     bf16x8 b0 = *reinterpret_cast<const bf16x8*>(Ks + KSWZ(r32, cb));
;     bf16x8 b1 = *reinterpret_cast<const bf16x8*>(Ks + KSWZ(32 + r32, cb));
;     p0 = __builtin_amdgcn_mfma_f32_32x32x16_bf16(b0, qr[d0], p0, 0, 0, 0);
;     p1 = __builtin_amdgcn_mfma_f32_32x32x16_bf16(b1, qr[d0], p1, 0, 0, 0); }
; }
; template <int DQK, int MODE, int ldq, int ldk, int ldv> ...
;     ...
;     __syncthreads(); SWRITE(0, SE);
;     RESC(alB); __syncthreads();
;     SBAR(); qkt<DQK>(pA0, pA1, K_lds, qr, r32, hi);
;     finishSM(pB0, pB1, alB, l_reg, pa0, pa1, pa2, pa3); SBAR();
;     if (j + 3 < NT) SLOAD(SE, j + 3); SBAR();
.LBB0_304:
	s_waitcnt lgkmcnt(0)
	s_barrier
	ds_read_b128 v[32:35], v148 offset:32768
	ds_read_b128 v[36:39], v148 offset:40960
	ds_read_b128 v[176:179], v152 offset:32768
	ds_read_b128 v[180:183], v152 offset:40960
	s_waitcnt lgkmcnt(3)
	v_mfma_f32_32x32x16_bf16 v[48:63], v[32:35], v[84:87], 0
	s_waitcnt lgkmcnt(2)
	v_mfma_f32_32x32x16_bf16 v[32:47], v[36:39], v[84:87], 0
	s_waitcnt lgkmcnt(1)
	v_mfma_f32_32x32x16_bf16 v[48:63], v[176:179], v[80:83], v[48:63]
	s_waitcnt lgkmcnt(0)
	v_mfma_f32_32x32x16_bf16 v[32:47], v[180:183], v[80:83], v[32:47]
	ds_read_b128 v[176:179], v151 offset:32768
	ds_read_b128 v[180:183], v151 offset:40960
	s_waitcnt lgkmcnt(1)
	v_mfma_f32_32x32x16_bf16 v[48:63], v[176:179], v[76:79], v[48:63]
	s_waitcnt lgkmcnt(0)
	v_mfma_f32_32x32x16_bf16 v[32:47], v[180:183], v[76:79], v[32:47]
	ds_read_b128 v[176:179], v149 offset:32768
	ds_read_b128 v[180:183], v149 offset:40960
	s_waitcnt lgkmcnt(1)
	v_mfma_f32_32x32x16_bf16 v[48:63], v[176:179], v[72:75], v[48:63]
	s_waitcnt lgkmcnt(0)
	v_mfma_f32_32x32x16_bf16 v[32:47], v[180:183], v[72:75], v[32:47]
	ds_read_b128 v[176:179], v150 offset:32768
	ds_read_b128 v[180:183], v150 offset:40960
	s_waitcnt lgkmcnt(1)
	v_mfma_f32_32x32x16_bf16 v[48:63], v[176:179], v[68:71], v[48:63]
	s_waitcnt lgkmcnt(0)
	v_mfma_f32_32x32x16_bf16 v[32:47], v[180:183], v[68:71], v[32:47]
	ds_read_b128 v[176:179], v153 offset:32768
	ds_read_b128 v[180:183], v153 offset:40960
	s_waitcnt vmcnt(0)
	ds_write_b128 v146, v[184:187] offset:49152
	ds_write_b128 v147, v[230:233] offset:49152
	ds_write_b128 v145, v[188:191]
	s_waitcnt lgkmcnt(4)
	v_mfma_f32_32x32x16_bf16 v[48:63], v[176:179], v[64:67], v[48:63]
	s_waitcnt lgkmcnt(3)
	v_mfma_f32_32x32x16_bf16 v[32:47], v[180:183], v[64:67], v[32:47]
	ds_read_b64_tr_b16 v[192:193], v143 offset:0
	ds_read_b64_tr_b16 v[194:195], v143 offset:0x800
	ds_read_b64_tr_b16 v[196:197], v143 offset:0x1000
	ds_read_b64_tr_b16 v[198:199], v143 offset:0x1800
	ds_read_b64_tr_b16 v[200:201], v143 offset:0x2000
	ds_read_b64_tr_b16 v[202:203], v143 offset:0x2800
	ds_read_b64_tr_b16 v[210:211], v143 offset:0x3000
	ds_read_b64_tr_b16 v[212:213], v143 offset:0x3800
	v_exp_f32_e32 v175, v164
	v_add_f32_e32 v164, 0, v112
	v_add_f32_e32 v164, v127, v164
	v_add_f32_e32 v164, v113, v164
	v_add_f32_e32 v164, v126, v164
	v_add_f32_e32 v164, v114, v164
	v_add_f32_e32 v164, v125, v164
	v_add_f32_e32 v164, v115, v164
	v_add_f32_e32 v164, v124, v164
	v_add_f32_e32 v164, v116, v164
	v_add_f32_e32 v164, v123, v164
	v_add_f32_e32 v164, v117, v164
	v_add_f32_e32 v164, v122, v164
	v_exp_f32_e32 v167, v167
	v_add_f32_e32 v164, v118, v164
	v_exp_f32_e32 v168, v168
	v_add_f32_e32 v164, v121, v164
	v_exp_f32_e32 v169, v169
	v_add_f32_e32 v164, v119, v164
	v_exp_f32_e32 v170, v170
	v_add_f32_e32 v164, v120, v164
	v_exp_f32_e32 v171, v171
	v_add_f32_e32 v164, v167, v164
	v_exp_f32_e32 v172, v172
	v_add_f32_e32 v164, v168, v164
	v_exp_f32_e32 v160, v160
	v_add_f32_e32 v164, v169, v164
	v_exp_f32_e32 v161, v161
	v_add_f32_e32 v164, v170, v164
	v_exp_f32_e32 v162, v162
	v_add_f32_e32 v164, v171, v164
	v_exp_f32_e32 v163, v163
	v_add_f32_e32 v164, v172, v164
	v_add_f32_e32 v164, v160, v164
	v_add_f32_e32 v164, v161, v164
	v_exp_f32_e32 v166, v166
	v_add_f32_e32 v164, v162, v164
	v_exp_f32_e32 v173, v173
	v_add_f32_e32 v164, v163, v164
	v_exp_f32_e32 v174, v174
	v_add_f32_e32 v164, v175, v164
	v_exp_f32_e32 v159, v159
	v_cvt_pk_bf16_f32 v214, v112, v127
	v_cvt_pk_bf16_f32 v215, v113, v126
	v_cvt_pk_bf16_f32 v216, v114, v125
	v_cvt_pk_bf16_f32 v217, v115, v124
	v_cvt_pk_bf16_f32 v218, v116, v123
	v_cvt_pk_bf16_f32 v219, v117, v122
	v_exp_f32_e32 v176, v165
	v_cvt_pk_bf16_f32 v220, v118, v121
	v_cvt_pk_bf16_f32 v221, v119, v120
	v_cvt_pk_bf16_f32 v222, v167, v168
	v_cvt_pk_bf16_f32 v223, v169, v170
	v_cvt_pk_bf16_f32 v224, v171, v172
	s_nop 0
	v_add_f32_e32 v164, v176, v164
	v_add_f32_e32 v164, v166, v164
	v_add_f32_e32 v164, v173, v164
	v_add_f32_e32 v164, v174, v164
	v_add_f32_e32 v164, v159, v164
	v_mov_b32_e32 v165, v164
	v_cvt_pk_bf16_f32 v225, v160, v161
	v_cvt_pk_bf16_f32 v226, v162, v163
	v_cvt_pk_bf16_f32 v227, v175, v176
	v_cvt_pk_bf16_f32 v228, v166, v173
	v_cvt_pk_bf16_f32 v229, v174, v159
	s_nop 1
	v_permlane32_swap_b32_e32 v164, v165
	v_permlane32_swap_b32_e32 v214, v216
	v_permlane32_swap_b32_e32 v215, v217
	v_permlane32_swap_b32_e32 v218, v220
	v_permlane32_swap_b32_e32 v219, v221
	v_permlane32_swap_b32_e32 v222, v224
	v_permlane32_swap_b32_e32 v223, v225
	v_permlane32_swap_b32_e32 v226, v228
	v_permlane32_swap_b32_e32 v227, v229
	s_cmpk_lt_u32 s25, 0x7e
	s_cselect_b32 s98, 0, 0xffffff80
	s_cselect_b32 s99, s10, s24
	s_add_i32 s98, s98, s11
	s_lshl_b32 s98, s98, 6
	s_add_i32 s98, s98, s99
	s_sub_i32 s98, s98, 64
	s_ashr_i32 s99, s98, 31
	v_lshl_add_u64 v[92:93], s[98:99], 0, v[130:131]
	v_lshlrev_b64 v[92:93], 9, v[92:93]
	v_lshl_add_u64 v[92:93], v[134:135], 0, v[92:93]
	global_load_dwordx4 v[92:95], v[92:93], off
	s_cmpk_gt_u32 s25, 0x80
	s_cbranch_scc1 .LBB0_306
	s_cmpk_lt_u32 s25, 0x7d
	s_cselect_b32 s0, 0, 0xffffff80
	s_cselect_b32 s1, s10, s24
	s_add_i32 s0, s0, s11
	s_lshl_b32 s0, s0, 6
	s_add_i32 s0, s0, s1
	s_ashr_i32 s1, s0, 31
	v_lshl_add_u64 v[88:89], s[0:1], 0, v[130:131]
	v_mad_u64_u32 v[90:91], s[12:13], v88, s70, v[136:137]
	v_or_b32_e32 v96, s0, v132
	v_mad_i32_i24 v91, v89, s70, v91
	v_mad_i64_i32 v[96:97], s[0:1], v96, s70, v[138:139]
	global_load_dwordx4 v[88:91], v[90:91], off
	s_nop 0
	s_nop 0
	global_load_dwordx4 v[96:99], v[96:97], off offset:128
; #define SBAR() __builtin_amdgcn_sched_barrier(0)
; template <int DQK> __device__ __forceinline__ void partialSM(f32x16& p0, f32x16& p1, float& m_reg, float& mn, float& alpha) {
;   constexpr float SCALE = (DQK == 96) ? 0.10206207261596577f : 0.125f;
;   constexpr float C = SCALE * 1.4426950408889634f;
;   float pmax = p0[0];
; #pragma unroll
;   for (int r = 1; r < 16; ++r) pmax = fmaxf(pmax, p0[r]);
; #pragma unroll
;   for (int r = 0; r < 16; ++r) pmax = fmaxf(pmax, p1[r]);
;   { auto rr = __builtin_amdgcn_permlane32_swap(__float_as_uint(pmax), __float_as_uint(pmax), false, false);
;     pmax = fmaxf(__uint_as_float(rr[0]), __uint_as_float(rr[1])); }
;   if (__builtin_expect(__all(pmax - m_reg <= THR / SCALE), 1)) { mn = m_reg; alpha = 1.f; }
;   else { mn = fmaxf(m_reg, pmax); alpha = __builtin_amdgcn_exp2f((m_reg - mn) * C); m_reg = mn; }
;   float mnC = -mn * C;
; #pragma unroll
;   for (int r = 0; r < 16; ++r) p0[r] = fmaf(p0[r], C, mnC);
; #pragma unroll
;   for (int r = 0; r < 16; ++r) p1[r] = fmaf(p1[r], C, mnC);
; #pragma unroll
;   for (int r = 0; r < 16; ++r) p0[r] = __builtin_amdgcn_exp2f(p0[r]);
; }
; template <int D0> __device__ __forceinline__ void pv_one(f32x16& od, int vb, bf16x8 pa0, bf16x8 pa1, bf16x8 pa2, bf16x8 pa3) {
;   const s16x4 l0 = tr_read<v_rd_off(D0, 0, 0)>(vb), h0 = tr_read<v_rd_off(D0, 0, 1)>(vb), l1 = tr_read<v_rd_off(D0, 1, 0)>(vb), h1 = tr_read<v_rd_off(D0, 1, 1)>(vb);
;   const s16x4 l2 = tr_read<v_rd_off(D0, 2, 0)>(vb), h2 = tr_read<v_rd_off(D0, 2, 1)>(vb), l3 = tr_read<v_rd_off(D0, 3, 0)>(vb), h3 = tr_read<v_rd_off(D0, 3, 1)>(vb);
;   asm volatile("s_waitcnt lgkmcnt(0)" ::: "memory"); SBAR();
;   od = __builtin_amdgcn_mfma_f32_32x32x16_bf16(pa0, PKLH(l0, h0), od, 0, 0, 0);
;   od = __builtin_amdgcn_mfma_f32_32x32x16_bf16(pa1, PKLH(l1, h1), od, 0, 0, 0);
;   od = __builtin_amdgcn_mfma_f32_32x32x16_bf16(pa2, PKLH(l2, h2), od, 0, 0, 0);
;   od = __builtin_amdgcn_mfma_f32_32x32x16_bf16(pa3, PKLH(l3, h3), od, 0, 0, 0);
; }
; __device__ __forceinline__ void pv_d0(f32x16* o, int vb, bf16x8 pa0, bf16x8 pa1, bf16x8 pa2, bf16x8 pa3) {
;   pv_one<0>(o[0], vb, pa0, pa1, pa2, pa3); pv_one<1>(o[1], vb, pa0, pa1, pa2, pa3);
; }
.LBB0_306:
	s_waitcnt lgkmcnt(0)
	s_nop 0
	v_mfma_f32_32x32x16_bf16 v[0:15], v[214:217], v[192:195], v[0:15]
	ds_read_b64_tr_b16 v[192:193], v143 offset:0x200
	ds_read_b64_tr_b16 v[194:195], v143 offset:0xa00
	v_max_f32_e32 v112, v48, v49
	v_max3_f32 v112, v112, v50, v51
	v_max3_f32 v112, v112, v52, v53
	v_max3_f32 v112, v112, v54, v55
	v_max3_f32 v112, v112, v56, v57
	v_max3_f32 v112, v112, v58, v59
	v_max3_f32 v112, v112, v60, v61
	v_max3_f32 v112, v112, v62, v63
	v_mfma_f32_32x32x16_bf16 v[0:15], v[218:221], v[196:199], v[0:15]
	ds_read_b64_tr_b16 v[196:197], v143 offset:0x1200
	ds_read_b64_tr_b16 v[198:199], v143 offset:0x1a00
	v_max3_f32 v112, v112, v32, v33
	v_max3_f32 v112, v112, v34, v35
	v_max3_f32 v112, v112, v36, v37
	v_max3_f32 v112, v112, v38, v39
	v_max3_f32 v112, v112, v40, v41
	v_max3_f32 v112, v112, v42, v43
	v_max3_f32 v112, v112, v44, v45
	v_max3_f32 v112, v112, v46, v47
	v_mfma_f32_32x32x16_bf16 v[0:15], v[222:225], v[200:203], v[0:15]
	ds_read_b64_tr_b16 v[200:201], v143 offset:0x2200
	ds_read_b64_tr_b16 v[202:203], v143 offset:0x2a00
	v_mov_b32_e32 v113, v112
	s_nop 1
	v_permlane32_swap_b32_e32 v112, v113
	v_max_f32_e32 v112, v112, v113
	v_sub_f32_e32 v113, v112, v158
	v_cmp_ge_f32_e32 vcc, s80, v113
	v_max_f32_e32 v112, v158, v112
	v_sub_f32_e32 v113, v158, v112
	v_mfma_f32_32x32x16_bf16 v[0:15], v[226:229], v[210:213], v[0:15]
	ds_read_b64_tr_b16 v[210:211], v143 offset:0x3200
	ds_read_b64_tr_b16 v[212:213], v143 offset:0x3a00
	v_mul_f32_e32 v113, 0x3e16c740, v113
	v_exp_f32_e32 v113, v113
	s_cmp_eq_u64 vcc, exec
	s_cselect_b64 s[0:1], -1, 0
	v_cndmask_b32_e64 v117, v113, 1.0, s[0:1]
	v_cmp_gt_f32_e32 vcc, 1.0, v117
	s_waitcnt lgkmcnt(0)
	v_mfma_f32_32x32x16_bf16 v[16:31], v[214:217], v[192:195], v[16:31]
	v_cndmask_b32_e64 v116, v112, v158, s[0:1]
	v_mul_f32_e32 v100, 0xbe16c740, v116
	v_mov_b32_e32 v101, v100
	v_fmamk_f32 v48, v48, 0x3e16c740, v100
	v_fmamk_f32 v49, v49, 0x3e16c740, v100
	v_fmamk_f32 v50, v50, 0x3e16c740, v100
	v_fmamk_f32 v51, v51, 0x3e16c740, v100
	v_fmamk_f32 v52, v52, 0x3e16c740, v100
	v_fmamk_f32 v53, v53, 0x3e16c740, v100
	v_fmamk_f32 v54, v54, 0x3e16c740, v100
	v_fmamk_f32 v55, v55, 0x3e16c740, v100
	v_fmamk_f32 v56, v56, 0x3e16c740, v100
	v_mfma_f32_32x32x16_bf16 v[16:31], v[218:221], v[196:199], v[16:31]
	v_fmamk_f32 v57, v57, 0x3e16c740, v100
	v_fmamk_f32 v58, v58, 0x3e16c740, v100
	v_fmamk_f32 v59, v59, 0x3e16c740, v100
	v_fmamk_f32 v60, v60, 0x3e16c740, v100
	v_fmamk_f32 v61, v61, 0x3e16c740, v100
	v_fmamk_f32 v62, v62, 0x3e16c740, v100
	v_fmac_f32_e32 v101, 0x3e16c740, v63
	v_exp_f32_e32 v126, v48
	v_exp_f32_e32 v160, v49
	v_exp_f32_e32 v127, v50
	v_exp_f32_e32 v161, v51
	v_exp_f32_e32 v158, v52
	v_mfma_f32_32x32x16_bf16 v[16:31], v[222:225], v[200:203], v[16:31]
	v_exp_f32_e32 v162, v53
	v_exp_f32_e32 v159, v54
	v_exp_f32_e32 v163, v55
	v_exp_f32_e32 v118, v56
	v_exp_f32_e32 v121, v57
	v_exp_f32_e32 v119, v58
	v_exp_f32_e32 v122, v59
	v_exp_f32_e32 v120, v60
	v_exp_f32_e32 v123, v61
	v_exp_f32_e32 v124, v62
	v_exp_f32_e32 v125, v101
	v_pk_fma_f32 v[114:115], v[32:33], s[40:41], v[100:101] op_sel_hi:[1,0,0]
	v_mfma_f32_32x32x16_bf16 v[16:31], v[226:229], v[210:213], v[16:31]
	v_add_f32_e32 v32, v155, v156
	v_fmac_f32_e32 v32, v154, v142
	v_add_f32_e32 v142, v164, v165
	v_pk_fma_f32 v[112:113], v[34:35], s[40:41], v[100:101] op_sel_hi:[1,0,0]
	v_pk_fma_f32 v[108:109], v[36:37], s[40:41], v[100:101] op_sel_hi:[1,0,0]
	v_pk_fma_f32 v[104:105], v[38:39], s[40:41], v[100:101] op_sel_hi:[1,0,0]
	v_pk_fma_f32 v[102:103], v[40:41], s[40:41], v[100:101] op_sel_hi:[1,0,0]
	v_pk_fma_f32 v[110:111], v[42:43], s[40:41], v[100:101] op_sel_hi:[1,0,0]
	v_pk_fma_f32 v[106:107], v[44:45], s[40:41], v[100:101] op_sel_hi:[1,0,0]
	v_pk_fma_f32 v[100:101], v[46:47], s[40:41], v[100:101] op_sel_hi:[1,0,0]
	v_fmac_f32_e32 v142, v32, v157
	s_cbranch_vccz .LBB0_310
	s_and_saveexec_b64 s[12:13], s[4:5]
	ds_write_b32 v141, v117 offset:128
	s_or_b64 exec, exec, s[12:13]
	s_waitcnt lgkmcnt(0)
	ds_read_b128 v[192:195], v129 offset:224
	ds_read_b128 v[196:199], v129 offset:192
	ds_read_b128 v[200:203], v129 offset:160
	ds_read_b128 v[210:213], v129 offset:128
	s_waitcnt lgkmcnt(3)
	v_pk_mul_f32 v[14:15], v[14:15], v[194:195]
	s_waitcnt lgkmcnt(2)
	v_pk_mul_f32 v[10:11], v[10:11], v[198:199]
	s_waitcnt lgkmcnt(1)
	v_pk_mul_f32 v[6:7], v[6:7], v[202:203]
	s_waitcnt lgkmcnt(0)
	v_pk_mul_f32 v[2:3], v[2:3], v[212:213]
	v_pk_mul_f32 v[12:13], v[12:13], v[192:193]
	v_pk_mul_f32 v[8:9], v[8:9], v[196:197]
	v_pk_mul_f32 v[4:5], v[4:5], v[200:201]
	v_pk_mul_f32 v[0:1], v[0:1], v[210:211]
	v_pk_mul_f32 v[30:31], v[30:31], v[194:195]
	v_pk_mul_f32 v[26:27], v[26:27], v[198:199]
	v_pk_mul_f32 v[22:23], v[22:23], v[202:203]
	v_pk_mul_f32 v[18:19], v[18:19], v[212:213]
	v_pk_mul_f32 v[28:29], v[28:29], v[192:193]
	v_pk_mul_f32 v[24:25], v[24:25], v[196:197]
	v_pk_mul_f32 v[20:21], v[20:21], v[200:201]
	v_pk_mul_f32 v[16:17], v[16:17], v[210:211]
